# phase-1 silu/fq/fk epilogue: per-element mode dispatch replaced by three straight-line variants (4 elements interleaved), unreachable blocks removed
# speedup vs baseline: 1.0363x; 1.0028x over previous
.LBB0_96:
	s_mov_b64 s[0:1], 0
	v_mov_b32_e32 v156, v176
	s_add_u32 s40, s96, s0
	s_addc_u32 s41, s97, s1
	v_lshrrev_b32_e32 v128, 6, v156
	v_ashrrev_i32_e32 v160, 8, v156
	v_bfe_u32 v157, v128, 1, 1
	v_bfe_u32 v158, v156, 6, 1
	v_bfe_u32 v159, v156, 5, 1
	v_and_b32_e32 v161, 31, v156
	s_and_b32 s48, s34, 0x700
	s_mov_b64 s[42:43], -1
	s_and_b64 vcc, exec, s[38:39]
	s_waitcnt vmcnt(0) lgkmcnt(0)
	s_barrier
	s_cbranch_vccz .LBB0_394
	s_cmp_gt_u32 s64, 5
	s_cbranch_scc0 .LBB0_391
	s_sub_i32 s0, s64, 18
	v_bfe_u32 v130, v156, 6, 2
	s_cmp_gt_u32 s0, -9
	s_cbranch_scc0 .LBB0_388
	v_lshl_or_b32 v133, v160, 7, v161
	v_lshlrev_b32_e32 v134, 3, v159
	v_lshl_or_b32 v134, v130, 7, v134
	v_mul_lo_u32 v133, v133, s55
	s_cmp_lt_u32 s64, 14
	v_add_u32_e32 v131, v134, v133
	s_cbranch_scc1 .Lp1e_silu
	s_cmp_lt_u32 s64, 16
	s_cbranch_scc1 .Lp1e_scale
	v_cvt_pk_bf16_f32 v128, v112, v113
	v_cvt_pk_bf16_f32 v129, v114, v115
	ds_write_b64 v131, v[128:129]
	v_cvt_pk_bf16_f32 v128, v116, v117
	v_cvt_pk_bf16_f32 v129, v118, v119
	ds_write_b64 v131, v[128:129] offset:16
	v_cvt_pk_bf16_f32 v128, v120, v121
	v_cvt_pk_bf16_f32 v129, v122, v123
	ds_write_b64 v131, v[128:129] offset:32
	v_cvt_pk_bf16_f32 v128, v124, v125
	v_cvt_pk_bf16_f32 v129, v126, v127
	ds_write_b64 v131, v[128:129] offset:48
	v_cvt_pk_bf16_f32 v128, v96, v97
	v_cvt_pk_bf16_f32 v129, v98, v99
	ds_write_b64 v131, v[128:129] offset:64
	v_cvt_pk_bf16_f32 v128, v100, v101
	v_cvt_pk_bf16_f32 v129, v102, v103
	ds_write_b64 v131, v[128:129] offset:80
	v_cvt_pk_bf16_f32 v128, v104, v105
	v_cvt_pk_bf16_f32 v129, v106, v107
	ds_write_b64 v131, v[128:129] offset:96
	v_cvt_pk_bf16_f32 v128, v108, v109
	v_cvt_pk_bf16_f32 v129, v110, v111
	ds_write_b64 v131, v[128:129] offset:112
	v_cvt_pk_bf16_f32 v128, v80, v81
	v_cvt_pk_bf16_f32 v129, v82, v83
	ds_write_b64 v131, v[128:129] offset:16896
	v_cvt_pk_bf16_f32 v128, v84, v85
	v_cvt_pk_bf16_f32 v129, v86, v87
	ds_write_b64 v131, v[128:129] offset:16912
	v_cvt_pk_bf16_f32 v128, v88, v89
	v_cvt_pk_bf16_f32 v129, v90, v91
	ds_write_b64 v131, v[128:129] offset:16928
	v_cvt_pk_bf16_f32 v128, v92, v93
	v_cvt_pk_bf16_f32 v129, v94, v95
	ds_write_b64 v131, v[128:129] offset:16944
	v_cvt_pk_bf16_f32 v128, v64, v65
	v_cvt_pk_bf16_f32 v129, v66, v67
	ds_write_b64 v131, v[128:129] offset:16960
	v_cvt_pk_bf16_f32 v128, v68, v69
	v_cvt_pk_bf16_f32 v129, v70, v71
	ds_write_b64 v131, v[128:129] offset:16976
	v_cvt_pk_bf16_f32 v128, v72, v73
	v_cvt_pk_bf16_f32 v129, v74, v75
	ds_write_b64 v131, v[128:129] offset:16992
	v_cvt_pk_bf16_f32 v128, v76, v77
	v_cvt_pk_bf16_f32 v129, v78, v79
	ds_write_b64 v131, v[128:129] offset:17008
	v_cvt_pk_bf16_f32 v128, v48, v49
	v_cvt_pk_bf16_f32 v129, v50, v51
	ds_write_b64 v131, v[128:129] offset:33792
	v_cvt_pk_bf16_f32 v128, v52, v53
	v_cvt_pk_bf16_f32 v129, v54, v55
	ds_write_b64 v131, v[128:129] offset:33808
	v_cvt_pk_bf16_f32 v128, v56, v57
	v_cvt_pk_bf16_f32 v129, v58, v59
	ds_write_b64 v131, v[128:129] offset:33824
	v_cvt_pk_bf16_f32 v128, v60, v61
	v_cvt_pk_bf16_f32 v129, v62, v63
	ds_write_b64 v131, v[128:129] offset:33840
	v_cvt_pk_bf16_f32 v128, v32, v33
	v_cvt_pk_bf16_f32 v129, v34, v35
	ds_write_b64 v131, v[128:129] offset:33856
	v_cvt_pk_bf16_f32 v128, v36, v37
	v_cvt_pk_bf16_f32 v129, v38, v39
	ds_write_b64 v131, v[128:129] offset:33872
	v_cvt_pk_bf16_f32 v128, v40, v41
	v_cvt_pk_bf16_f32 v129, v42, v43
	ds_write_b64 v131, v[128:129] offset:33888
	v_cvt_pk_bf16_f32 v128, v44, v45
	v_cvt_pk_bf16_f32 v129, v46, v47
	ds_write_b64 v131, v[128:129] offset:33904
	v_cvt_pk_bf16_f32 v128, v16, v17
	v_cvt_pk_bf16_f32 v129, v18, v19
	ds_write_b64 v131, v[128:129] offset:50688
	v_cvt_pk_bf16_f32 v128, v20, v21
	v_cvt_pk_bf16_f32 v129, v22, v23
	ds_write_b64 v131, v[128:129] offset:50704
	v_cvt_pk_bf16_f32 v128, v24, v25
	v_cvt_pk_bf16_f32 v129, v26, v27
	ds_write_b64 v131, v[128:129] offset:50720
	v_cvt_pk_bf16_f32 v128, v28, v29
	v_cvt_pk_bf16_f32 v129, v30, v31
	ds_write_b64 v131, v[128:129] offset:50736
	v_cvt_pk_bf16_f32 v128, v0, v1
	v_cvt_pk_bf16_f32 v129, v2, v3
	ds_write_b64 v131, v[128:129] offset:50752
	v_cvt_pk_bf16_f32 v128, v4, v5
	v_cvt_pk_bf16_f32 v129, v6, v7
	ds_write_b64 v131, v[128:129] offset:50768
	v_cvt_pk_bf16_f32 v128, v8, v9
	v_cvt_pk_bf16_f32 v129, v10, v11
	ds_write_b64 v131, v[128:129] offset:50784
	v_cvt_pk_bf16_f32 v128, v12, v13
	v_cvt_pk_bf16_f32 v129, v14, v15
	ds_write_b64 v131, v[128:129] offset:50800
	s_branch .Lp1e_done
.Lp1e_scale:
	v_mul_f32_e32 v132, 0x3e000000, v112
	v_mul_f32_e32 v133, 0x3e000000, v113
	v_mul_f32_e32 v134, 0x3e000000, v114
	v_mul_f32_e32 v135, 0x3e000000, v115
	v_cvt_pk_bf16_f32 v128, v132, v133
	v_cvt_pk_bf16_f32 v129, v134, v135
	ds_write_b64 v131, v[128:129]
	v_mul_f32_e32 v132, 0x3e000000, v116
	v_mul_f32_e32 v133, 0x3e000000, v117
	v_mul_f32_e32 v134, 0x3e000000, v118
	v_mul_f32_e32 v135, 0x3e000000, v119
	v_cvt_pk_bf16_f32 v128, v132, v133
	v_cvt_pk_bf16_f32 v129, v134, v135
	ds_write_b64 v131, v[128:129] offset:16
	v_mul_f32_e32 v132, 0x3e000000, v120
	v_mul_f32_e32 v133, 0x3e000000, v121
	v_mul_f32_e32 v134, 0x3e000000, v122
	v_mul_f32_e32 v135, 0x3e000000, v123
	v_cvt_pk_bf16_f32 v128, v132, v133
	v_cvt_pk_bf16_f32 v129, v134, v135
	ds_write_b64 v131, v[128:129] offset:32
	v_mul_f32_e32 v132, 0x3e000000, v124
	v_mul_f32_e32 v133, 0x3e000000, v125
	v_mul_f32_e32 v134, 0x3e000000, v126
	v_mul_f32_e32 v135, 0x3e000000, v127
	v_cvt_pk_bf16_f32 v128, v132, v133
	v_cvt_pk_bf16_f32 v129, v134, v135
	ds_write_b64 v131, v[128:129] offset:48
	v_mul_f32_e32 v132, 0x3e000000, v96
	v_mul_f32_e32 v133, 0x3e000000, v97
	v_mul_f32_e32 v134, 0x3e000000, v98
	v_mul_f32_e32 v135, 0x3e000000, v99
	v_cvt_pk_bf16_f32 v128, v132, v133
	v_cvt_pk_bf16_f32 v129, v134, v135
	ds_write_b64 v131, v[128:129] offset:64
	v_mul_f32_e32 v132, 0x3e000000, v100
	v_mul_f32_e32 v133, 0x3e000000, v101
	v_mul_f32_e32 v134, 0x3e000000, v102
	v_mul_f32_e32 v135, 0x3e000000, v103
	v_cvt_pk_bf16_f32 v128, v132, v133
	v_cvt_pk_bf16_f32 v129, v134, v135
	ds_write_b64 v131, v[128:129] offset:80
	v_mul_f32_e32 v132, 0x3e000000, v104
	v_mul_f32_e32 v133, 0x3e000000, v105
	v_mul_f32_e32 v134, 0x3e000000, v106
	v_mul_f32_e32 v135, 0x3e000000, v107
	v_cvt_pk_bf16_f32 v128, v132, v133
	v_cvt_pk_bf16_f32 v129, v134, v135
	ds_write_b64 v131, v[128:129] offset:96
	v_mul_f32_e32 v132, 0x3e000000, v108
	v_mul_f32_e32 v133, 0x3e000000, v109
	v_mul_f32_e32 v134, 0x3e000000, v110
	v_mul_f32_e32 v135, 0x3e000000, v111
	v_cvt_pk_bf16_f32 v128, v132, v133
	v_cvt_pk_bf16_f32 v129, v134, v135
	ds_write_b64 v131, v[128:129] offset:112
	v_mul_f32_e32 v132, 0x3e000000, v80
	v_mul_f32_e32 v133, 0x3e000000, v81
	v_mul_f32_e32 v134, 0x3e000000, v82
	v_mul_f32_e32 v135, 0x3e000000, v83
	v_cvt_pk_bf16_f32 v128, v132, v133
	v_cvt_pk_bf16_f32 v129, v134, v135
	ds_write_b64 v131, v[128:129] offset:16896
	v_mul_f32_e32 v132, 0x3e000000, v84
	v_mul_f32_e32 v133, 0x3e000000, v85
	v_mul_f32_e32 v134, 0x3e000000, v86
	v_mul_f32_e32 v135, 0x3e000000, v87
	v_cvt_pk_bf16_f32 v128, v132, v133
	v_cvt_pk_bf16_f32 v129, v134, v135
	ds_write_b64 v131, v[128:129] offset:16912
	v_mul_f32_e32 v132, 0x3e000000, v88
	v_mul_f32_e32 v133, 0x3e000000, v89
	v_mul_f32_e32 v134, 0x3e000000, v90
	v_mul_f32_e32 v135, 0x3e000000, v91
	v_cvt_pk_bf16_f32 v128, v132, v133
	v_cvt_pk_bf16_f32 v129, v134, v135
	ds_write_b64 v131, v[128:129] offset:16928
	v_mul_f32_e32 v132, 0x3e000000, v92
	v_mul_f32_e32 v133, 0x3e000000, v93
	v_mul_f32_e32 v134, 0x3e000000, v94
	v_mul_f32_e32 v135, 0x3e000000, v95
	v_cvt_pk_bf16_f32 v128, v132, v133
	v_cvt_pk_bf16_f32 v129, v134, v135
	ds_write_b64 v131, v[128:129] offset:16944
	v_mul_f32_e32 v132, 0x3e000000, v64
	v_mul_f32_e32 v133, 0x3e000000, v65
	v_mul_f32_e32 v134, 0x3e000000, v66
	v_mul_f32_e32 v135, 0x3e000000, v67
	v_cvt_pk_bf16_f32 v128, v132, v133
	v_cvt_pk_bf16_f32 v129, v134, v135
	ds_write_b64 v131, v[128:129] offset:16960
	v_mul_f32_e32 v132, 0x3e000000, v68
	v_mul_f32_e32 v133, 0x3e000000, v69
	v_mul_f32_e32 v134, 0x3e000000, v70
	v_mul_f32_e32 v135, 0x3e000000, v71
	v_cvt_pk_bf16_f32 v128, v132, v133
	v_cvt_pk_bf16_f32 v129, v134, v135
	ds_write_b64 v131, v[128:129] offset:16976
	v_mul_f32_e32 v132, 0x3e000000, v72
	v_mul_f32_e32 v133, 0x3e000000, v73
	v_mul_f32_e32 v134, 0x3e000000, v74
	v_mul_f32_e32 v135, 0x3e000000, v75
	v_cvt_pk_bf16_f32 v128, v132, v133
	v_cvt_pk_bf16_f32 v129, v134, v135
	ds_write_b64 v131, v[128:129] offset:16992
	v_mul_f32_e32 v132, 0x3e000000, v76
	v_mul_f32_e32 v133, 0x3e000000, v77
	v_mul_f32_e32 v134, 0x3e000000, v78
	v_mul_f32_e32 v135, 0x3e000000, v79
	v_cvt_pk_bf16_f32 v128, v132, v133
	v_cvt_pk_bf16_f32 v129, v134, v135
	ds_write_b64 v131, v[128:129] offset:17008
	v_mul_f32_e32 v132, 0x3e000000, v48
	v_mul_f32_e32 v133, 0x3e000000, v49
	v_mul_f32_e32 v134, 0x3e000000, v50
	v_mul_f32_e32 v135, 0x3e000000, v51
	v_cvt_pk_bf16_f32 v128, v132, v133
	v_cvt_pk_bf16_f32 v129, v134, v135
	ds_write_b64 v131, v[128:129] offset:33792
	v_mul_f32_e32 v132, 0x3e000000, v52
	v_mul_f32_e32 v133, 0x3e000000, v53
	v_mul_f32_e32 v134, 0x3e000000, v54
	v_mul_f32_e32 v135, 0x3e000000, v55
	v_cvt_pk_bf16_f32 v128, v132, v133
	v_cvt_pk_bf16_f32 v129, v134, v135
	ds_write_b64 v131, v[128:129] offset:33808
	v_mul_f32_e32 v132, 0x3e000000, v56
	v_mul_f32_e32 v133, 0x3e000000, v57
	v_mul_f32_e32 v134, 0x3e000000, v58
	v_mul_f32_e32 v135, 0x3e000000, v59
	v_cvt_pk_bf16_f32 v128, v132, v133
	v_cvt_pk_bf16_f32 v129, v134, v135
	ds_write_b64 v131, v[128:129] offset:33824
	v_mul_f32_e32 v132, 0x3e000000, v60
	v_mul_f32_e32 v133, 0x3e000000, v61
	v_mul_f32_e32 v134, 0x3e000000, v62
	v_mul_f32_e32 v135, 0x3e000000, v63
	v_cvt_pk_bf16_f32 v128, v132, v133
	v_cvt_pk_bf16_f32 v129, v134, v135
	ds_write_b64 v131, v[128:129] offset:33840
	v_mul_f32_e32 v132, 0x3e000000, v32
	v_mul_f32_e32 v133, 0x3e000000, v33
	v_mul_f32_e32 v134, 0x3e000000, v34
	v_mul_f32_e32 v135, 0x3e000000, v35
	v_cvt_pk_bf16_f32 v128, v132, v133
	v_cvt_pk_bf16_f32 v129, v134, v135
	ds_write_b64 v131, v[128:129] offset:33856
	v_mul_f32_e32 v132, 0x3e000000, v36
	v_mul_f32_e32 v133, 0x3e000000, v37
	v_mul_f32_e32 v134, 0x3e000000, v38
	v_mul_f32_e32 v135, 0x3e000000, v39
	v_cvt_pk_bf16_f32 v128, v132, v133
	v_cvt_pk_bf16_f32 v129, v134, v135
	ds_write_b64 v131, v[128:129] offset:33872
	v_mul_f32_e32 v132, 0x3e000000, v40
	v_mul_f32_e32 v133, 0x3e000000, v41
	v_mul_f32_e32 v134, 0x3e000000, v42
	v_mul_f32_e32 v135, 0x3e000000, v43
	v_cvt_pk_bf16_f32 v128, v132, v133
	v_cvt_pk_bf16_f32 v129, v134, v135
	ds_write_b64 v131, v[128:129] offset:33888
	v_mul_f32_e32 v132, 0x3e000000, v44
	v_mul_f32_e32 v133, 0x3e000000, v45
	v_mul_f32_e32 v134, 0x3e000000, v46
	v_mul_f32_e32 v135, 0x3e000000, v47
	v_cvt_pk_bf16_f32 v128, v132, v133
	v_cvt_pk_bf16_f32 v129, v134, v135
	ds_write_b64 v131, v[128:129] offset:33904
	v_mul_f32_e32 v132, 0x3e000000, v16
	v_mul_f32_e32 v133, 0x3e000000, v17
	v_mul_f32_e32 v134, 0x3e000000, v18
	v_mul_f32_e32 v135, 0x3e000000, v19
	v_cvt_pk_bf16_f32 v128, v132, v133
	v_cvt_pk_bf16_f32 v129, v134, v135
	ds_write_b64 v131, v[128:129] offset:50688
	v_mul_f32_e32 v132, 0x3e000000, v20
	v_mul_f32_e32 v133, 0x3e000000, v21
	v_mul_f32_e32 v134, 0x3e000000, v22
	v_mul_f32_e32 v135, 0x3e000000, v23
	v_cvt_pk_bf16_f32 v128, v132, v133
	v_cvt_pk_bf16_f32 v129, v134, v135
	ds_write_b64 v131, v[128:129] offset:50704
	v_mul_f32_e32 v132, 0x3e000000, v24
	v_mul_f32_e32 v133, 0x3e000000, v25
	v_mul_f32_e32 v134, 0x3e000000, v26
	v_mul_f32_e32 v135, 0x3e000000, v27
	v_cvt_pk_bf16_f32 v128, v132, v133
	v_cvt_pk_bf16_f32 v129, v134, v135
	ds_write_b64 v131, v[128:129] offset:50720
	v_mul_f32_e32 v132, 0x3e000000, v28
	v_mul_f32_e32 v133, 0x3e000000, v29
	v_mul_f32_e32 v134, 0x3e000000, v30
	v_mul_f32_e32 v135, 0x3e000000, v31
	v_cvt_pk_bf16_f32 v128, v132, v133
	v_cvt_pk_bf16_f32 v129, v134, v135
	ds_write_b64 v131, v[128:129] offset:50736
	v_mul_f32_e32 v132, 0x3e000000, v0
	v_mul_f32_e32 v133, 0x3e000000, v1
	v_mul_f32_e32 v134, 0x3e000000, v2
	v_mul_f32_e32 v135, 0x3e000000, v3
	v_cvt_pk_bf16_f32 v128, v132, v133
	v_cvt_pk_bf16_f32 v129, v134, v135
	ds_write_b64 v131, v[128:129] offset:50752
	v_mul_f32_e32 v132, 0x3e000000, v4
	v_mul_f32_e32 v133, 0x3e000000, v5
	v_mul_f32_e32 v134, 0x3e000000, v6
	v_mul_f32_e32 v135, 0x3e000000, v7
	v_cvt_pk_bf16_f32 v128, v132, v133
	v_cvt_pk_bf16_f32 v129, v134, v135
	ds_write_b64 v131, v[128:129] offset:50768
	v_mul_f32_e32 v132, 0x3e000000, v8
	v_mul_f32_e32 v133, 0x3e000000, v9
	v_mul_f32_e32 v134, 0x3e000000, v10
	v_mul_f32_e32 v135, 0x3e000000, v11
	v_cvt_pk_bf16_f32 v128, v132, v133
	v_cvt_pk_bf16_f32 v129, v134, v135
	ds_write_b64 v131, v[128:129] offset:50784
	v_mul_f32_e32 v132, 0x3e000000, v12
	v_mul_f32_e32 v133, 0x3e000000, v13
	v_mul_f32_e32 v134, 0x3e000000, v14
	v_mul_f32_e32 v135, 0x3e000000, v15
	v_cvt_pk_bf16_f32 v128, v132, v133
	v_cvt_pk_bf16_f32 v129, v134, v135
	ds_write_b64 v131, v[128:129] offset:50800
	s_branch .Lp1e_done
.Lp1e_silu:
	v_mul_f32_e32 v132, 0xbfb8aa3b, v112
	v_mul_f32_e32 v133, 0xbfb8aa3b, v113
	v_mul_f32_e32 v134, 0xbfb8aa3b, v114
	v_mul_f32_e32 v135, 0xbfb8aa3b, v115
	v_exp_f32_e32 v132, v132
	v_exp_f32_e32 v133, v133
	v_exp_f32_e32 v134, v134
	v_exp_f32_e32 v135, v135
	v_add_f32_e32 v132, 1.0, v132
	v_add_f32_e32 v133, 1.0, v133
	v_add_f32_e32 v134, 1.0, v134
	v_add_f32_e32 v135, 1.0, v135
	v_rcp_f32_e32 v132, v132
	v_rcp_f32_e32 v133, v133
	v_rcp_f32_e32 v134, v134
	v_rcp_f32_e32 v135, v135
	v_mul_f32_e32 v132, v112, v132
	v_mul_f32_e32 v133, v113, v133
	v_mul_f32_e32 v134, v114, v134
	v_mul_f32_e32 v135, v115, v135
	v_cvt_pk_bf16_f32 v128, v132, v133
	v_cvt_pk_bf16_f32 v129, v134, v135
	ds_write_b64 v131, v[128:129]
	v_mul_f32_e32 v132, 0xbfb8aa3b, v116
	v_mul_f32_e32 v133, 0xbfb8aa3b, v117
	v_mul_f32_e32 v134, 0xbfb8aa3b, v118
	v_mul_f32_e32 v135, 0xbfb8aa3b, v119
	v_exp_f32_e32 v132, v132
	v_exp_f32_e32 v133, v133
	v_exp_f32_e32 v134, v134
	v_exp_f32_e32 v135, v135
	v_add_f32_e32 v132, 1.0, v132
	v_add_f32_e32 v133, 1.0, v133
	v_add_f32_e32 v134, 1.0, v134
	v_add_f32_e32 v135, 1.0, v135
	v_rcp_f32_e32 v132, v132
	v_rcp_f32_e32 v133, v133
	v_rcp_f32_e32 v134, v134
	v_rcp_f32_e32 v135, v135
	v_mul_f32_e32 v132, v116, v132
	v_mul_f32_e32 v133, v117, v133
	v_mul_f32_e32 v134, v118, v134
	v_mul_f32_e32 v135, v119, v135
	v_cvt_pk_bf16_f32 v128, v132, v133
	v_cvt_pk_bf16_f32 v129, v134, v135
	ds_write_b64 v131, v[128:129] offset:16
	v_mul_f32_e32 v132, 0xbfb8aa3b, v120
	v_mul_f32_e32 v133, 0xbfb8aa3b, v121
	v_mul_f32_e32 v134, 0xbfb8aa3b, v122
	v_mul_f32_e32 v135, 0xbfb8aa3b, v123
	v_exp_f32_e32 v132, v132
	v_exp_f32_e32 v133, v133
	v_exp_f32_e32 v134, v134
	v_exp_f32_e32 v135, v135
	v_add_f32_e32 v132, 1.0, v132
	v_add_f32_e32 v133, 1.0, v133
	v_add_f32_e32 v134, 1.0, v134
	v_add_f32_e32 v135, 1.0, v135
	v_rcp_f32_e32 v132, v132
	v_rcp_f32_e32 v133, v133
	v_rcp_f32_e32 v134, v134
	v_rcp_f32_e32 v135, v135
	v_mul_f32_e32 v132, v120, v132
	v_mul_f32_e32 v133, v121, v133
	v_mul_f32_e32 v134, v122, v134
	v_mul_f32_e32 v135, v123, v135
	v_cvt_pk_bf16_f32 v128, v132, v133
	v_cvt_pk_bf16_f32 v129, v134, v135
	ds_write_b64 v131, v[128:129] offset:32
	v_mul_f32_e32 v132, 0xbfb8aa3b, v124
	v_mul_f32_e32 v133, 0xbfb8aa3b, v125
	v_mul_f32_e32 v134, 0xbfb8aa3b, v126
	v_mul_f32_e32 v135, 0xbfb8aa3b, v127
	v_exp_f32_e32 v132, v132
	v_exp_f32_e32 v133, v133
	v_exp_f32_e32 v134, v134
	v_exp_f32_e32 v135, v135
	v_add_f32_e32 v132, 1.0, v132
	v_add_f32_e32 v133, 1.0, v133
	v_add_f32_e32 v134, 1.0, v134
	v_add_f32_e32 v135, 1.0, v135
	v_rcp_f32_e32 v132, v132
	v_rcp_f32_e32 v133, v133
	v_rcp_f32_e32 v134, v134
	v_rcp_f32_e32 v135, v135
	v_mul_f32_e32 v132, v124, v132
	v_mul_f32_e32 v133, v125, v133
	v_mul_f32_e32 v134, v126, v134
	v_mul_f32_e32 v135, v127, v135
	v_cvt_pk_bf16_f32 v128, v132, v133
	v_cvt_pk_bf16_f32 v129, v134, v135
	ds_write_b64 v131, v[128:129] offset:48
	v_mul_f32_e32 v132, 0xbfb8aa3b, v96
	v_mul_f32_e32 v133, 0xbfb8aa3b, v97
	v_mul_f32_e32 v134, 0xbfb8aa3b, v98
	v_mul_f32_e32 v135, 0xbfb8aa3b, v99
	v_exp_f32_e32 v132, v132
	v_exp_f32_e32 v133, v133
	v_exp_f32_e32 v134, v134
	v_exp_f32_e32 v135, v135
	v_add_f32_e32 v132, 1.0, v132
	v_add_f32_e32 v133, 1.0, v133
	v_add_f32_e32 v134, 1.0, v134
	v_add_f32_e32 v135, 1.0, v135
	v_rcp_f32_e32 v132, v132
	v_rcp_f32_e32 v133, v133
	v_rcp_f32_e32 v134, v134
	v_rcp_f32_e32 v135, v135
	v_mul_f32_e32 v132, v96, v132
	v_mul_f32_e32 v133, v97, v133
	v_mul_f32_e32 v134, v98, v134
	v_mul_f32_e32 v135, v99, v135
	v_cvt_pk_bf16_f32 v128, v132, v133
	v_cvt_pk_bf16_f32 v129, v134, v135
	ds_write_b64 v131, v[128:129] offset:64
	v_mul_f32_e32 v132, 0xbfb8aa3b, v100
	v_mul_f32_e32 v133, 0xbfb8aa3b, v101
	v_mul_f32_e32 v134, 0xbfb8aa3b, v102
	v_mul_f32_e32 v135, 0xbfb8aa3b, v103
	v_exp_f32_e32 v132, v132
	v_exp_f32_e32 v133, v133
	v_exp_f32_e32 v134, v134
	v_exp_f32_e32 v135, v135
	v_add_f32_e32 v132, 1.0, v132
	v_add_f32_e32 v133, 1.0, v133
	v_add_f32_e32 v134, 1.0, v134
	v_add_f32_e32 v135, 1.0, v135
	v_rcp_f32_e32 v132, v132
	v_rcp_f32_e32 v133, v133
	v_rcp_f32_e32 v134, v134
	v_rcp_f32_e32 v135, v135
	v_mul_f32_e32 v132, v100, v132
	v_mul_f32_e32 v133, v101, v133
	v_mul_f32_e32 v134, v102, v134
	v_mul_f32_e32 v135, v103, v135
	v_cvt_pk_bf16_f32 v128, v132, v133
	v_cvt_pk_bf16_f32 v129, v134, v135
	ds_write_b64 v131, v[128:129] offset:80
	v_mul_f32_e32 v132, 0xbfb8aa3b, v104
	v_mul_f32_e32 v133, 0xbfb8aa3b, v105
	v_mul_f32_e32 v134, 0xbfb8aa3b, v106
	v_mul_f32_e32 v135, 0xbfb8aa3b, v107
	v_exp_f32_e32 v132, v132
	v_exp_f32_e32 v133, v133
	v_exp_f32_e32 v134, v134
	v_exp_f32_e32 v135, v135
	v_add_f32_e32 v132, 1.0, v132
	v_add_f32_e32 v133, 1.0, v133
	v_add_f32_e32 v134, 1.0, v134
	v_add_f32_e32 v135, 1.0, v135
	v_rcp_f32_e32 v132, v132
	v_rcp_f32_e32 v133, v133
	v_rcp_f32_e32 v134, v134
	v_rcp_f32_e32 v135, v135
	v_mul_f32_e32 v132, v104, v132
	v_mul_f32_e32 v133, v105, v133
	v_mul_f32_e32 v134, v106, v134
	v_mul_f32_e32 v135, v107, v135
	v_cvt_pk_bf16_f32 v128, v132, v133
	v_cvt_pk_bf16_f32 v129, v134, v135
	ds_write_b64 v131, v[128:129] offset:96
	v_mul_f32_e32 v132, 0xbfb8aa3b, v108
	v_mul_f32_e32 v133, 0xbfb8aa3b, v109
	v_mul_f32_e32 v134, 0xbfb8aa3b, v110
	v_mul_f32_e32 v135, 0xbfb8aa3b, v111
	v_exp_f32_e32 v132, v132
	v_exp_f32_e32 v133, v133
	v_exp_f32_e32 v134, v134
	v_exp_f32_e32 v135, v135
	v_add_f32_e32 v132, 1.0, v132
	v_add_f32_e32 v133, 1.0, v133
	v_add_f32_e32 v134, 1.0, v134
	v_add_f32_e32 v135, 1.0, v135
	v_rcp_f32_e32 v132, v132
	v_rcp_f32_e32 v133, v133
	v_rcp_f32_e32 v134, v134
	v_rcp_f32_e32 v135, v135
	v_mul_f32_e32 v132, v108, v132
	v_mul_f32_e32 v133, v109, v133
	v_mul_f32_e32 v134, v110, v134
	v_mul_f32_e32 v135, v111, v135
	v_cvt_pk_bf16_f32 v128, v132, v133
	v_cvt_pk_bf16_f32 v129, v134, v135
	ds_write_b64 v131, v[128:129] offset:112
	v_mul_f32_e32 v132, 0xbfb8aa3b, v80
	v_mul_f32_e32 v133, 0xbfb8aa3b, v81
	v_mul_f32_e32 v134, 0xbfb8aa3b, v82
	v_mul_f32_e32 v135, 0xbfb8aa3b, v83
	v_exp_f32_e32 v132, v132
	v_exp_f32_e32 v133, v133
	v_exp_f32_e32 v134, v134
	v_exp_f32_e32 v135, v135
	v_add_f32_e32 v132, 1.0, v132
	v_add_f32_e32 v133, 1.0, v133
	v_add_f32_e32 v134, 1.0, v134
	v_add_f32_e32 v135, 1.0, v135
	v_rcp_f32_e32 v132, v132
	v_rcp_f32_e32 v133, v133
	v_rcp_f32_e32 v134, v134
	v_rcp_f32_e32 v135, v135
	v_mul_f32_e32 v132, v80, v132
	v_mul_f32_e32 v133, v81, v133
	v_mul_f32_e32 v134, v82, v134
	v_mul_f32_e32 v135, v83, v135
	v_cvt_pk_bf16_f32 v128, v132, v133
	v_cvt_pk_bf16_f32 v129, v134, v135
	ds_write_b64 v131, v[128:129] offset:16896
	v_mul_f32_e32 v132, 0xbfb8aa3b, v84
	v_mul_f32_e32 v133, 0xbfb8aa3b, v85
	v_mul_f32_e32 v134, 0xbfb8aa3b, v86
	v_mul_f32_e32 v135, 0xbfb8aa3b, v87
	v_exp_f32_e32 v132, v132
	v_exp_f32_e32 v133, v133
	v_exp_f32_e32 v134, v134
	v_exp_f32_e32 v135, v135
	v_add_f32_e32 v132, 1.0, v132
	v_add_f32_e32 v133, 1.0, v133
	v_add_f32_e32 v134, 1.0, v134
	v_add_f32_e32 v135, 1.0, v135
	v_rcp_f32_e32 v132, v132
	v_rcp_f32_e32 v133, v133
	v_rcp_f32_e32 v134, v134
	v_rcp_f32_e32 v135, v135
	v_mul_f32_e32 v132, v84, v132
	v_mul_f32_e32 v133, v85, v133
	v_mul_f32_e32 v134, v86, v134
	v_mul_f32_e32 v135, v87, v135
	v_cvt_pk_bf16_f32 v128, v132, v133
	v_cvt_pk_bf16_f32 v129, v134, v135
	ds_write_b64 v131, v[128:129] offset:16912
	v_mul_f32_e32 v132, 0xbfb8aa3b, v88
	v_mul_f32_e32 v133, 0xbfb8aa3b, v89
	v_mul_f32_e32 v134, 0xbfb8aa3b, v90
	v_mul_f32_e32 v135, 0xbfb8aa3b, v91
	v_exp_f32_e32 v132, v132
	v_exp_f32_e32 v133, v133
	v_exp_f32_e32 v134, v134
	v_exp_f32_e32 v135, v135
	v_add_f32_e32 v132, 1.0, v132
	v_add_f32_e32 v133, 1.0, v133
	v_add_f32_e32 v134, 1.0, v134
	v_add_f32_e32 v135, 1.0, v135
	v_rcp_f32_e32 v132, v132
	v_rcp_f32_e32 v133, v133
	v_rcp_f32_e32 v134, v134
	v_rcp_f32_e32 v135, v135
	v_mul_f32_e32 v132, v88, v132
	v_mul_f32_e32 v133, v89, v133
	v_mul_f32_e32 v134, v90, v134
	v_mul_f32_e32 v135, v91, v135
	v_cvt_pk_bf16_f32 v128, v132, v133
	v_cvt_pk_bf16_f32 v129, v134, v135
	ds_write_b64 v131, v[128:129] offset:16928
	v_mul_f32_e32 v132, 0xbfb8aa3b, v92
	v_mul_f32_e32 v133, 0xbfb8aa3b, v93
	v_mul_f32_e32 v134, 0xbfb8aa3b, v94
	v_mul_f32_e32 v135, 0xbfb8aa3b, v95
	v_exp_f32_e32 v132, v132
	v_exp_f32_e32 v133, v133
	v_exp_f32_e32 v134, v134
	v_exp_f32_e32 v135, v135
	v_add_f32_e32 v132, 1.0, v132
	v_add_f32_e32 v133, 1.0, v133
	v_add_f32_e32 v134, 1.0, v134
	v_add_f32_e32 v135, 1.0, v135
	v_rcp_f32_e32 v132, v132
	v_rcp_f32_e32 v133, v133
	v_rcp_f32_e32 v134, v134
	v_rcp_f32_e32 v135, v135
	v_mul_f32_e32 v132, v92, v132
	v_mul_f32_e32 v133, v93, v133
	v_mul_f32_e32 v134, v94, v134
	v_mul_f32_e32 v135, v95, v135
	v_cvt_pk_bf16_f32 v128, v132, v133
	v_cvt_pk_bf16_f32 v129, v134, v135
	ds_write_b64 v131, v[128:129] offset:16944
	v_mul_f32_e32 v132, 0xbfb8aa3b, v64
	v_mul_f32_e32 v133, 0xbfb8aa3b, v65
	v_mul_f32_e32 v134, 0xbfb8aa3b, v66
	v_mul_f32_e32 v135, 0xbfb8aa3b, v67
	v_exp_f32_e32 v132, v132
	v_exp_f32_e32 v133, v133
	v_exp_f32_e32 v134, v134
	v_exp_f32_e32 v135, v135
	v_add_f32_e32 v132, 1.0, v132
	v_add_f32_e32 v133, 1.0, v133
	v_add_f32_e32 v134, 1.0, v134
	v_add_f32_e32 v135, 1.0, v135
	v_rcp_f32_e32 v132, v132
	v_rcp_f32_e32 v133, v133
	v_rcp_f32_e32 v134, v134
	v_rcp_f32_e32 v135, v135
	v_mul_f32_e32 v132, v64, v132
	v_mul_f32_e32 v133, v65, v133
	v_mul_f32_e32 v134, v66, v134
	v_mul_f32_e32 v135, v67, v135
	v_cvt_pk_bf16_f32 v128, v132, v133
	v_cvt_pk_bf16_f32 v129, v134, v135
	ds_write_b64 v131, v[128:129] offset:16960
	v_mul_f32_e32 v132, 0xbfb8aa3b, v68
	v_mul_f32_e32 v133, 0xbfb8aa3b, v69
	v_mul_f32_e32 v134, 0xbfb8aa3b, v70
	v_mul_f32_e32 v135, 0xbfb8aa3b, v71
	v_exp_f32_e32 v132, v132
	v_exp_f32_e32 v133, v133
	v_exp_f32_e32 v134, v134
	v_exp_f32_e32 v135, v135
	v_add_f32_e32 v132, 1.0, v132
	v_add_f32_e32 v133, 1.0, v133
	v_add_f32_e32 v134, 1.0, v134
	v_add_f32_e32 v135, 1.0, v135
	v_rcp_f32_e32 v132, v132
	v_rcp_f32_e32 v133, v133
	v_rcp_f32_e32 v134, v134
	v_rcp_f32_e32 v135, v135
	v_mul_f32_e32 v132, v68, v132
	v_mul_f32_e32 v133, v69, v133
	v_mul_f32_e32 v134, v70, v134
	v_mul_f32_e32 v135, v71, v135
	v_cvt_pk_bf16_f32 v128, v132, v133
	v_cvt_pk_bf16_f32 v129, v134, v135
	ds_write_b64 v131, v[128:129] offset:16976
	v_mul_f32_e32 v132, 0xbfb8aa3b, v72
	v_mul_f32_e32 v133, 0xbfb8aa3b, v73
	v_mul_f32_e32 v134, 0xbfb8aa3b, v74
	v_mul_f32_e32 v135, 0xbfb8aa3b, v75
	v_exp_f32_e32 v132, v132
	v_exp_f32_e32 v133, v133
	v_exp_f32_e32 v134, v134
	v_exp_f32_e32 v135, v135
	v_add_f32_e32 v132, 1.0, v132
	v_add_f32_e32 v133, 1.0, v133
	v_add_f32_e32 v134, 1.0, v134
	v_add_f32_e32 v135, 1.0, v135
	v_rcp_f32_e32 v132, v132
	v_rcp_f32_e32 v133, v133
	v_rcp_f32_e32 v134, v134
	v_rcp_f32_e32 v135, v135
	v_mul_f32_e32 v132, v72, v132
	v_mul_f32_e32 v133, v73, v133
	v_mul_f32_e32 v134, v74, v134
	v_mul_f32_e32 v135, v75, v135
	v_cvt_pk_bf16_f32 v128, v132, v133
	v_cvt_pk_bf16_f32 v129, v134, v135
	ds_write_b64 v131, v[128:129] offset:16992
	v_mul_f32_e32 v132, 0xbfb8aa3b, v76
	v_mul_f32_e32 v133, 0xbfb8aa3b, v77
	v_mul_f32_e32 v134, 0xbfb8aa3b, v78
	v_mul_f32_e32 v135, 0xbfb8aa3b, v79
	v_exp_f32_e32 v132, v132
	v_exp_f32_e32 v133, v133
	v_exp_f32_e32 v134, v134
	v_exp_f32_e32 v135, v135
	v_add_f32_e32 v132, 1.0, v132
	v_add_f32_e32 v133, 1.0, v133
	v_add_f32_e32 v134, 1.0, v134
	v_add_f32_e32 v135, 1.0, v135
	v_rcp_f32_e32 v132, v132
	v_rcp_f32_e32 v133, v133
	v_rcp_f32_e32 v134, v134
	v_rcp_f32_e32 v135, v135
	v_mul_f32_e32 v132, v76, v132
	v_mul_f32_e32 v133, v77, v133
	v_mul_f32_e32 v134, v78, v134
	v_mul_f32_e32 v135, v79, v135
	v_cvt_pk_bf16_f32 v128, v132, v133
	v_cvt_pk_bf16_f32 v129, v134, v135
	ds_write_b64 v131, v[128:129] offset:17008
	v_mul_f32_e32 v132, 0xbfb8aa3b, v48
	v_mul_f32_e32 v133, 0xbfb8aa3b, v49
	v_mul_f32_e32 v134, 0xbfb8aa3b, v50
	v_mul_f32_e32 v135, 0xbfb8aa3b, v51
	v_exp_f32_e32 v132, v132
	v_exp_f32_e32 v133, v133
	v_exp_f32_e32 v134, v134
	v_exp_f32_e32 v135, v135
	v_add_f32_e32 v132, 1.0, v132
	v_add_f32_e32 v133, 1.0, v133
	v_add_f32_e32 v134, 1.0, v134
	v_add_f32_e32 v135, 1.0, v135
	v_rcp_f32_e32 v132, v132
	v_rcp_f32_e32 v133, v133
	v_rcp_f32_e32 v134, v134
	v_rcp_f32_e32 v135, v135
	v_mul_f32_e32 v132, v48, v132
	v_mul_f32_e32 v133, v49, v133
	v_mul_f32_e32 v134, v50, v134
	v_mul_f32_e32 v135, v51, v135
	v_cvt_pk_bf16_f32 v128, v132, v133
	v_cvt_pk_bf16_f32 v129, v134, v135
	ds_write_b64 v131, v[128:129] offset:33792
	v_mul_f32_e32 v132, 0xbfb8aa3b, v52
	v_mul_f32_e32 v133, 0xbfb8aa3b, v53
	v_mul_f32_e32 v134, 0xbfb8aa3b, v54
	v_mul_f32_e32 v135, 0xbfb8aa3b, v55
	v_exp_f32_e32 v132, v132
	v_exp_f32_e32 v133, v133
	v_exp_f32_e32 v134, v134
	v_exp_f32_e32 v135, v135
	v_add_f32_e32 v132, 1.0, v132
	v_add_f32_e32 v133, 1.0, v133
	v_add_f32_e32 v134, 1.0, v134
	v_add_f32_e32 v135, 1.0, v135
	v_rcp_f32_e32 v132, v132
	v_rcp_f32_e32 v133, v133
	v_rcp_f32_e32 v134, v134
	v_rcp_f32_e32 v135, v135
	v_mul_f32_e32 v132, v52, v132
	v_mul_f32_e32 v133, v53, v133
	v_mul_f32_e32 v134, v54, v134
	v_mul_f32_e32 v135, v55, v135
	v_cvt_pk_bf16_f32 v128, v132, v133
	v_cvt_pk_bf16_f32 v129, v134, v135
	ds_write_b64 v131, v[128:129] offset:33808
	v_mul_f32_e32 v132, 0xbfb8aa3b, v56
	v_mul_f32_e32 v133, 0xbfb8aa3b, v57
	v_mul_f32_e32 v134, 0xbfb8aa3b, v58
	v_mul_f32_e32 v135, 0xbfb8aa3b, v59
	v_exp_f32_e32 v132, v132
	v_exp_f32_e32 v133, v133
	v_exp_f32_e32 v134, v134
	v_exp_f32_e32 v135, v135
	v_add_f32_e32 v132, 1.0, v132
	v_add_f32_e32 v133, 1.0, v133
	v_add_f32_e32 v134, 1.0, v134
	v_add_f32_e32 v135, 1.0, v135
	v_rcp_f32_e32 v132, v132
	v_rcp_f32_e32 v133, v133
	v_rcp_f32_e32 v134, v134
	v_rcp_f32_e32 v135, v135
	v_mul_f32_e32 v132, v56, v132
	v_mul_f32_e32 v133, v57, v133
	v_mul_f32_e32 v134, v58, v134
	v_mul_f32_e32 v135, v59, v135
	v_cvt_pk_bf16_f32 v128, v132, v133
	v_cvt_pk_bf16_f32 v129, v134, v135
	ds_write_b64 v131, v[128:129] offset:33824
	v_mul_f32_e32 v132, 0xbfb8aa3b, v60
	v_mul_f32_e32 v133, 0xbfb8aa3b, v61
	v_mul_f32_e32 v134, 0xbfb8aa3b, v62
	v_mul_f32_e32 v135, 0xbfb8aa3b, v63
	v_exp_f32_e32 v132, v132
	v_exp_f32_e32 v133, v133
	v_exp_f32_e32 v134, v134
	v_exp_f32_e32 v135, v135
	v_add_f32_e32 v132, 1.0, v132
	v_add_f32_e32 v133, 1.0, v133
	v_add_f32_e32 v134, 1.0, v134
	v_add_f32_e32 v135, 1.0, v135
	v_rcp_f32_e32 v132, v132
	v_rcp_f32_e32 v133, v133
	v_rcp_f32_e32 v134, v134
	v_rcp_f32_e32 v135, v135
	v_mul_f32_e32 v132, v60, v132
	v_mul_f32_e32 v133, v61, v133
	v_mul_f32_e32 v134, v62, v134
	v_mul_f32_e32 v135, v63, v135
	v_cvt_pk_bf16_f32 v128, v132, v133
	v_cvt_pk_bf16_f32 v129, v134, v135
	ds_write_b64 v131, v[128:129] offset:33840
	v_mul_f32_e32 v132, 0xbfb8aa3b, v32
	v_mul_f32_e32 v133, 0xbfb8aa3b, v33
	v_mul_f32_e32 v134, 0xbfb8aa3b, v34
	v_mul_f32_e32 v135, 0xbfb8aa3b, v35
	v_exp_f32_e32 v132, v132
	v_exp_f32_e32 v133, v133
	v_exp_f32_e32 v134, v134
	v_exp_f32_e32 v135, v135
	v_add_f32_e32 v132, 1.0, v132
	v_add_f32_e32 v133, 1.0, v133
	v_add_f32_e32 v134, 1.0, v134
	v_add_f32_e32 v135, 1.0, v135
	v_rcp_f32_e32 v132, v132
	v_rcp_f32_e32 v133, v133
	v_rcp_f32_e32 v134, v134
	v_rcp_f32_e32 v135, v135
	v_mul_f32_e32 v132, v32, v132
	v_mul_f32_e32 v133, v33, v133
	v_mul_f32_e32 v134, v34, v134
	v_mul_f32_e32 v135, v35, v135
	v_cvt_pk_bf16_f32 v128, v132, v133
	v_cvt_pk_bf16_f32 v129, v134, v135
	ds_write_b64 v131, v[128:129] offset:33856
	v_mul_f32_e32 v132, 0xbfb8aa3b, v36
	v_mul_f32_e32 v133, 0xbfb8aa3b, v37
	v_mul_f32_e32 v134, 0xbfb8aa3b, v38
	v_mul_f32_e32 v135, 0xbfb8aa3b, v39
	v_exp_f32_e32 v132, v132
	v_exp_f32_e32 v133, v133
	v_exp_f32_e32 v134, v134
	v_exp_f32_e32 v135, v135
	v_add_f32_e32 v132, 1.0, v132
	v_add_f32_e32 v133, 1.0, v133
	v_add_f32_e32 v134, 1.0, v134
	v_add_f32_e32 v135, 1.0, v135
	v_rcp_f32_e32 v132, v132
	v_rcp_f32_e32 v133, v133
	v_rcp_f32_e32 v134, v134
	v_rcp_f32_e32 v135, v135
	v_mul_f32_e32 v132, v36, v132
	v_mul_f32_e32 v133, v37, v133
	v_mul_f32_e32 v134, v38, v134
	v_mul_f32_e32 v135, v39, v135
	v_cvt_pk_bf16_f32 v128, v132, v133
	v_cvt_pk_bf16_f32 v129, v134, v135
	ds_write_b64 v131, v[128:129] offset:33872
	v_mul_f32_e32 v132, 0xbfb8aa3b, v40
	v_mul_f32_e32 v133, 0xbfb8aa3b, v41
	v_mul_f32_e32 v134, 0xbfb8aa3b, v42
	v_mul_f32_e32 v135, 0xbfb8aa3b, v43
	v_exp_f32_e32 v132, v132
	v_exp_f32_e32 v133, v133
	v_exp_f32_e32 v134, v134
	v_exp_f32_e32 v135, v135
	v_add_f32_e32 v132, 1.0, v132
	v_add_f32_e32 v133, 1.0, v133
	v_add_f32_e32 v134, 1.0, v134
	v_add_f32_e32 v135, 1.0, v135
	v_rcp_f32_e32 v132, v132
	v_rcp_f32_e32 v133, v133
	v_rcp_f32_e32 v134, v134
	v_rcp_f32_e32 v135, v135
	v_mul_f32_e32 v132, v40, v132
	v_mul_f32_e32 v133, v41, v133
	v_mul_f32_e32 v134, v42, v134
	v_mul_f32_e32 v135, v43, v135
	v_cvt_pk_bf16_f32 v128, v132, v133
	v_cvt_pk_bf16_f32 v129, v134, v135
	ds_write_b64 v131, v[128:129] offset:33888
	v_mul_f32_e32 v132, 0xbfb8aa3b, v44
	v_mul_f32_e32 v133, 0xbfb8aa3b, v45
	v_mul_f32_e32 v134, 0xbfb8aa3b, v46
	v_mul_f32_e32 v135, 0xbfb8aa3b, v47
	v_exp_f32_e32 v132, v132
	v_exp_f32_e32 v133, v133
	v_exp_f32_e32 v134, v134
	v_exp_f32_e32 v135, v135
	v_add_f32_e32 v132, 1.0, v132
	v_add_f32_e32 v133, 1.0, v133
	v_add_f32_e32 v134, 1.0, v134
	v_add_f32_e32 v135, 1.0, v135
	v_rcp_f32_e32 v132, v132
	v_rcp_f32_e32 v133, v133
	v_rcp_f32_e32 v134, v134
	v_rcp_f32_e32 v135, v135
	v_mul_f32_e32 v132, v44, v132
	v_mul_f32_e32 v133, v45, v133
	v_mul_f32_e32 v134, v46, v134
	v_mul_f32_e32 v135, v47, v135
	v_cvt_pk_bf16_f32 v128, v132, v133
	v_cvt_pk_bf16_f32 v129, v134, v135
	ds_write_b64 v131, v[128:129] offset:33904
	v_mul_f32_e32 v132, 0xbfb8aa3b, v16
	v_mul_f32_e32 v133, 0xbfb8aa3b, v17
	v_mul_f32_e32 v134, 0xbfb8aa3b, v18
	v_mul_f32_e32 v135, 0xbfb8aa3b, v19
	v_exp_f32_e32 v132, v132
	v_exp_f32_e32 v133, v133
	v_exp_f32_e32 v134, v134
	v_exp_f32_e32 v135, v135
	v_add_f32_e32 v132, 1.0, v132
	v_add_f32_e32 v133, 1.0, v133
	v_add_f32_e32 v134, 1.0, v134
	v_add_f32_e32 v135, 1.0, v135
	v_rcp_f32_e32 v132, v132
	v_rcp_f32_e32 v133, v133
	v_rcp_f32_e32 v134, v134
	v_rcp_f32_e32 v135, v135
	v_mul_f32_e32 v132, v16, v132
	v_mul_f32_e32 v133, v17, v133
	v_mul_f32_e32 v134, v18, v134
	v_mul_f32_e32 v135, v19, v135
	v_cvt_pk_bf16_f32 v128, v132, v133
	v_cvt_pk_bf16_f32 v129, v134, v135
	ds_write_b64 v131, v[128:129] offset:50688
	v_mul_f32_e32 v132, 0xbfb8aa3b, v20
	v_mul_f32_e32 v133, 0xbfb8aa3b, v21
	v_mul_f32_e32 v134, 0xbfb8aa3b, v22
	v_mul_f32_e32 v135, 0xbfb8aa3b, v23
	v_exp_f32_e32 v132, v132
	v_exp_f32_e32 v133, v133
	v_exp_f32_e32 v134, v134
	v_exp_f32_e32 v135, v135
	v_add_f32_e32 v132, 1.0, v132
	v_add_f32_e32 v133, 1.0, v133
	v_add_f32_e32 v134, 1.0, v134
	v_add_f32_e32 v135, 1.0, v135
	v_rcp_f32_e32 v132, v132
	v_rcp_f32_e32 v133, v133
	v_rcp_f32_e32 v134, v134
	v_rcp_f32_e32 v135, v135
	v_mul_f32_e32 v132, v20, v132
	v_mul_f32_e32 v133, v21, v133
	v_mul_f32_e32 v134, v22, v134
	v_mul_f32_e32 v135, v23, v135
	v_cvt_pk_bf16_f32 v128, v132, v133
	v_cvt_pk_bf16_f32 v129, v134, v135
	ds_write_b64 v131, v[128:129] offset:50704
	v_mul_f32_e32 v132, 0xbfb8aa3b, v24
	v_mul_f32_e32 v133, 0xbfb8aa3b, v25
	v_mul_f32_e32 v134, 0xbfb8aa3b, v26
	v_mul_f32_e32 v135, 0xbfb8aa3b, v27
	v_exp_f32_e32 v132, v132
	v_exp_f32_e32 v133, v133
	v_exp_f32_e32 v134, v134
	v_exp_f32_e32 v135, v135
	v_add_f32_e32 v132, 1.0, v132
	v_add_f32_e32 v133, 1.0, v133
	v_add_f32_e32 v134, 1.0, v134
	v_add_f32_e32 v135, 1.0, v135
	v_rcp_f32_e32 v132, v132
	v_rcp_f32_e32 v133, v133
	v_rcp_f32_e32 v134, v134
	v_rcp_f32_e32 v135, v135
	v_mul_f32_e32 v132, v24, v132
	v_mul_f32_e32 v133, v25, v133
	v_mul_f32_e32 v134, v26, v134
	v_mul_f32_e32 v135, v27, v135
	v_cvt_pk_bf16_f32 v128, v132, v133
	v_cvt_pk_bf16_f32 v129, v134, v135
	ds_write_b64 v131, v[128:129] offset:50720
	v_mul_f32_e32 v132, 0xbfb8aa3b, v28
	v_mul_f32_e32 v133, 0xbfb8aa3b, v29
	v_mul_f32_e32 v134, 0xbfb8aa3b, v30
	v_mul_f32_e32 v135, 0xbfb8aa3b, v31
	v_exp_f32_e32 v132, v132
	v_exp_f32_e32 v133, v133
	v_exp_f32_e32 v134, v134
	v_exp_f32_e32 v135, v135
	v_add_f32_e32 v132, 1.0, v132
	v_add_f32_e32 v133, 1.0, v133
	v_add_f32_e32 v134, 1.0, v134
	v_add_f32_e32 v135, 1.0, v135
	v_rcp_f32_e32 v132, v132
	v_rcp_f32_e32 v133, v133
	v_rcp_f32_e32 v134, v134
	v_rcp_f32_e32 v135, v135
	v_mul_f32_e32 v132, v28, v132
	v_mul_f32_e32 v133, v29, v133
	v_mul_f32_e32 v134, v30, v134
	v_mul_f32_e32 v135, v31, v135
	v_cvt_pk_bf16_f32 v128, v132, v133
	v_cvt_pk_bf16_f32 v129, v134, v135
	ds_write_b64 v131, v[128:129] offset:50736
	v_mul_f32_e32 v132, 0xbfb8aa3b, v0
	v_mul_f32_e32 v133, 0xbfb8aa3b, v1
	v_mul_f32_e32 v134, 0xbfb8aa3b, v2
	v_mul_f32_e32 v135, 0xbfb8aa3b, v3
	v_exp_f32_e32 v132, v132
	v_exp_f32_e32 v133, v133
	v_exp_f32_e32 v134, v134
	v_exp_f32_e32 v135, v135
	v_add_f32_e32 v132, 1.0, v132
	v_add_f32_e32 v133, 1.0, v133
	v_add_f32_e32 v134, 1.0, v134
	v_add_f32_e32 v135, 1.0, v135
	v_rcp_f32_e32 v132, v132
	v_rcp_f32_e32 v133, v133
	v_rcp_f32_e32 v134, v134
	v_rcp_f32_e32 v135, v135
	v_mul_f32_e32 v132, v0, v132
	v_mul_f32_e32 v133, v1, v133
	v_mul_f32_e32 v134, v2, v134
	v_mul_f32_e32 v135, v3, v135
	v_cvt_pk_bf16_f32 v128, v132, v133
	v_cvt_pk_bf16_f32 v129, v134, v135
	ds_write_b64 v131, v[128:129] offset:50752
	v_mul_f32_e32 v132, 0xbfb8aa3b, v4
	v_mul_f32_e32 v133, 0xbfb8aa3b, v5
	v_mul_f32_e32 v134, 0xbfb8aa3b, v6
	v_mul_f32_e32 v135, 0xbfb8aa3b, v7
	v_exp_f32_e32 v132, v132
	v_exp_f32_e32 v133, v133
	v_exp_f32_e32 v134, v134
	v_exp_f32_e32 v135, v135
	v_add_f32_e32 v132, 1.0, v132
	v_add_f32_e32 v133, 1.0, v133
	v_add_f32_e32 v134, 1.0, v134
	v_add_f32_e32 v135, 1.0, v135
	v_rcp_f32_e32 v132, v132
	v_rcp_f32_e32 v133, v133
	v_rcp_f32_e32 v134, v134
	v_rcp_f32_e32 v135, v135
	v_mul_f32_e32 v132, v4, v132
	v_mul_f32_e32 v133, v5, v133
	v_mul_f32_e32 v134, v6, v134
	v_mul_f32_e32 v135, v7, v135
	v_cvt_pk_bf16_f32 v128, v132, v133
	v_cvt_pk_bf16_f32 v129, v134, v135
	ds_write_b64 v131, v[128:129] offset:50768
	v_mul_f32_e32 v132, 0xbfb8aa3b, v8
	v_mul_f32_e32 v133, 0xbfb8aa3b, v9
	v_mul_f32_e32 v134, 0xbfb8aa3b, v10
	v_mul_f32_e32 v135, 0xbfb8aa3b, v11
	v_exp_f32_e32 v132, v132
	v_exp_f32_e32 v133, v133
	v_exp_f32_e32 v134, v134
	v_exp_f32_e32 v135, v135
	v_add_f32_e32 v132, 1.0, v132
	v_add_f32_e32 v133, 1.0, v133
	v_add_f32_e32 v134, 1.0, v134
	v_add_f32_e32 v135, 1.0, v135
	v_rcp_f32_e32 v132, v132
	v_rcp_f32_e32 v133, v133
	v_rcp_f32_e32 v134, v134
	v_rcp_f32_e32 v135, v135
	v_mul_f32_e32 v132, v8, v132
	v_mul_f32_e32 v133, v9, v133
	v_mul_f32_e32 v134, v10, v134
	v_mul_f32_e32 v135, v11, v135
	v_cvt_pk_bf16_f32 v128, v132, v133
	v_cvt_pk_bf16_f32 v129, v134, v135
	ds_write_b64 v131, v[128:129] offset:50784
	v_mul_f32_e32 v132, 0xbfb8aa3b, v12
	v_mul_f32_e32 v133, 0xbfb8aa3b, v13
	v_mul_f32_e32 v134, 0xbfb8aa3b, v14
	v_mul_f32_e32 v135, 0xbfb8aa3b, v15
	v_exp_f32_e32 v132, v132
	v_exp_f32_e32 v133, v133
	v_exp_f32_e32 v134, v134
	v_exp_f32_e32 v135, v135
	v_add_f32_e32 v132, 1.0, v132
	v_add_f32_e32 v133, 1.0, v133
	v_add_f32_e32 v134, 1.0, v134
	v_add_f32_e32 v135, 1.0, v135
	v_rcp_f32_e32 v132, v132
	v_rcp_f32_e32 v133, v133
	v_rcp_f32_e32 v134, v134
	v_rcp_f32_e32 v135, v135
	v_mul_f32_e32 v132, v12, v132
	v_mul_f32_e32 v133, v13, v133
	v_mul_f32_e32 v134, v14, v134
	v_mul_f32_e32 v135, v15, v135
	v_cvt_pk_bf16_f32 v128, v132, v133
	v_cvt_pk_bf16_f32 v129, v134, v135
	ds_write_b64 v131, v[128:129] offset:50800
.Lp1e_done:
	s_mov_b64 s[42:43], 0
.LBB0_388:
	s_and_b64 vcc, exec, s[42:43]
	s_cbranch_vccz .LBB0_390
	v_lshlrev_b32_e32 v129, 3, v159
	v_lshl_or_b32 v128, v130, 6, v161
	v_and_or_b32 v129, v156, s56, v129
	v_mad_u32_u24 v132, v128, s55, v129
	v_cvt_pk_bf16_f32 v128, v112, v113
	v_cvt_pk_bf16_f32 v129, v114, v115
	v_cvt_pk_bf16_f32 v130, v116, v117
	v_cvt_pk_bf16_f32 v131, v118, v119
	ds_write2_b64 v132, v[128:129], v[130:131] offset1:2
	v_cvt_pk_bf16_f32 v128, v120, v121
	v_cvt_pk_bf16_f32 v129, v122, v123
	v_cvt_pk_bf16_f32 v130, v124, v125
	v_cvt_pk_bf16_f32 v131, v126, v127
	ds_write2_b64 v132, v[128:129], v[130:131] offset0:4 offset1:6
	v_cvt_pk_bf16_f32 v128, v80, v81
	v_cvt_pk_bf16_f32 v129, v82, v83
	v_cvt_pk_bf16_f32 v130, v84, v85
	v_cvt_pk_bf16_f32 v131, v86, v87
	v_add_u32_e32 v133, 0x4000, v132
	ds_write2_b64 v133, v[128:129], v[130:131] offset0:64 offset1:66
	v_cvt_pk_bf16_f32 v128, v88, v89
	v_cvt_pk_bf16_f32 v129, v90, v91
	v_cvt_pk_bf16_f32 v130, v92, v93
	v_cvt_pk_bf16_f32 v131, v94, v95
	ds_write2_b64 v133, v[128:129], v[130:131] offset0:68 offset1:70
	v_cvt_pk_bf16_f32 v128, v48, v49
	v_cvt_pk_bf16_f32 v129, v50, v51
	v_cvt_pk_bf16_f32 v130, v52, v53
	v_cvt_pk_bf16_f32 v131, v54, v55
	ds_write2_b64 v132, v[128:129], v[130:131] offset0:8 offset1:10
	v_cvt_pk_bf16_f32 v128, v56, v57
	v_cvt_pk_bf16_f32 v129, v58, v59
	v_cvt_pk_bf16_f32 v130, v60, v61
	v_cvt_pk_bf16_f32 v131, v62, v63
	ds_write2_b64 v132, v[128:129], v[130:131] offset0:12 offset1:14
	v_cvt_pk_bf16_f32 v128, v16, v17
	v_cvt_pk_bf16_f32 v129, v18, v19
	v_cvt_pk_bf16_f32 v130, v20, v21
	v_cvt_pk_bf16_f32 v131, v22, v23
	ds_write2_b64 v133, v[128:129], v[130:131] offset0:72 offset1:74
	v_cvt_pk_bf16_f32 v128, v24, v25
	v_cvt_pk_bf16_f32 v129, v26, v27
	v_cvt_pk_bf16_f32 v130, v28, v29
	v_cvt_pk_bf16_f32 v131, v30, v31
	ds_write2_b64 v133, v[128:129], v[130:131] offset0:76 offset1:78
	v_cvt_pk_bf16_f32 v128, v96, v97
	v_cvt_pk_bf16_f32 v129, v98, v99
	v_cvt_pk_bf16_f32 v130, v100, v101
	v_cvt_pk_bf16_f32 v131, v102, v103
	ds_write2_b64 v132, v[128:129], v[130:131] offset0:16 offset1:18
	v_cvt_pk_bf16_f32 v128, v104, v105
	v_cvt_pk_bf16_f32 v129, v106, v107
	v_cvt_pk_bf16_f32 v130, v108, v109
	v_cvt_pk_bf16_f32 v131, v110, v111
	ds_write2_b64 v132, v[128:129], v[130:131] offset0:20 offset1:22
	v_cvt_pk_bf16_f32 v128, v64, v65
	v_cvt_pk_bf16_f32 v129, v66, v67
	v_cvt_pk_bf16_f32 v130, v68, v69
	v_cvt_pk_bf16_f32 v131, v70, v71
	ds_write2_b64 v133, v[128:129], v[130:131] offset0:80 offset1:82
	v_cvt_pk_bf16_f32 v128, v72, v73
	v_cvt_pk_bf16_f32 v129, v74, v75
	v_cvt_pk_bf16_f32 v130, v76, v77
	v_cvt_pk_bf16_f32 v131, v78, v79
	ds_write2_b64 v133, v[128:129], v[130:131] offset0:84 offset1:86
	v_cvt_pk_bf16_f32 v128, v32, v33
	v_cvt_pk_bf16_f32 v129, v34, v35
	v_cvt_pk_bf16_f32 v130, v36, v37
	v_cvt_pk_bf16_f32 v131, v38, v39
	ds_write2_b64 v132, v[128:129], v[130:131] offset0:24 offset1:26
	v_cvt_pk_bf16_f32 v128, v40, v41
	v_cvt_pk_bf16_f32 v129, v42, v43
	v_cvt_pk_bf16_f32 v130, v44, v45
	v_cvt_pk_bf16_f32 v131, v46, v47
	ds_write2_b64 v132, v[128:129], v[130:131] offset0:28 offset1:30
	v_cvt_pk_bf16_f32 v128, v0, v1
	v_cvt_pk_bf16_f32 v129, v2, v3
	v_cvt_pk_bf16_f32 v130, v4, v5
	v_cvt_pk_bf16_f32 v131, v6, v7
	ds_write2_b64 v133, v[128:129], v[130:131] offset0:88 offset1:90
	v_cvt_pk_bf16_f32 v128, v8, v9
	v_cvt_pk_bf16_f32 v129, v10, v11
	v_cvt_pk_bf16_f32 v130, v12, v13
	v_cvt_pk_bf16_f32 v131, v14, v15
	ds_write2_b64 v133, v[128:129], v[130:131] offset0:92 offset1:94

.LBB0_425:
	v_add_u32_e32 v2, s0, v156
	v_add_u32_e32 v5, 0x200, v2
	v_add_u32_e32 v6, 0x400, v2
	v_ashrrev_i32_e32 v4, 5, v2
	v_add_u32_e32 v7, 0x600, v2
	v_ashrrev_i32_e32 v10, 5, v5
	v_ashrrev_i32_e32 v12, 5, v6
	v_ashrrev_i32_e32 v8, 31, v4
	v_ashrrev_i32_e32 v13, 5, v7
	v_mad_u64_u32 v[6:7], s[34:35], v10, s55, v[136:137]
	v_ashrrev_i32_e32 v16, 31, v10
	v_mul_lo_u32 v26, s43, v10
	v_mad_u64_u32 v[20:21], s[34:35], s42, v10, 0
	v_mad_u64_u32 v[10:11], s[34:35], v12, s55, v[136:137]
	v_mad_u64_u32 v[2:3], s[34:35], v4, s55, v[136:137]
	v_mul_lo_u32 v9, s43, v4
	v_mad_u64_u32 v[18:19], s[34:35], s42, v4, 0
	v_mul_lo_u32 v8, s42, v8
	v_ashrrev_i32_e32 v11, 31, v12
	v_mad_u64_u32 v[14:15], s[34:35], v13, s55, v[136:137]
	ds_read_b128 v[2:5], v2
	v_mul_lo_u32 v27, s43, v12
	v_mad_u64_u32 v[22:23], s[34:35], s42, v12, 0
	v_ashrrev_i32_e32 v28, 31, v13
	v_mul_lo_u32 v29, s43, v13
	v_mad_u64_u32 v[24:25], s[34:35], s42, v13, 0
	v_add3_u32 v19, v19, v8, v9
	ds_read_b128 v[6:9], v6
	v_mul_lo_u32 v30, s42, v16
	v_mul_lo_u32 v31, s42, v11
	ds_read_b128 v[10:13], v10
	ds_read_b128 v[14:17], v14
	s_addk_i32 s0, 0x800
	v_mul_lo_u32 v28, s42, v28
	s_cmpk_lg_i32 s0, 0x2000
	v_lshl_add_u64 v[18:19], v[18:19], 1, v[0:1]
	v_add3_u32 v21, v21, v30, v26
	v_add3_u32 v23, v23, v31, v27
	v_add3_u32 v25, v25, v28, v29
	v_lshl_add_u64 v[20:21], v[20:21], 1, v[0:1]
	v_lshl_add_u64 v[22:23], v[22:23], 1, v[0:1]
	v_lshl_add_u64 v[24:25], v[24:25], 1, v[0:1]
	s_waitcnt lgkmcnt(3)
	global_store_dwordx4 v[18:19], v[2:5], off
	s_waitcnt lgkmcnt(2)
	global_store_dwordx4 v[20:21], v[6:9], off
	s_waitcnt lgkmcnt(1)
	global_store_dwordx4 v[22:23], v[10:13], off
	s_waitcnt lgkmcnt(0)
	global_store_dwordx4 v[24:25], v[14:17], off
	s_cbranch_scc1 .LBB0_425
	s_add_i32 s53, s53, 1
	s_cmp_eq_u32 s53, s31
	s_cbranch_scc0 .LBB0_77
	s_branch .LBB0_907
.LBB0_907:
	s_barrier
	s_and_saveexec_b64 s[4:5], s[68:69]
	s_cbranch_execz .LBB0_917
	buffer_wbl2 sc1
	s_waitcnt vmcnt(0)
	s_load_dwordx2 s[6:7], s[92:93], 0x58
	v_mov_b32_e32 v2, 0
	s_mov_b64 s[8:9], exec
	v_mbcnt_lo_u32_b32 v1, s8, 0
	v_mbcnt_hi_u32_b32 v1, s9, v1
	s_waitcnt lgkmcnt(0)
	global_load_dword v0, v2, s[6:7] offset:40
	v_cmp_eq_u32_e32 vcc, 0, v1
	s_and_saveexec_b64 s[10:11], vcc
	s_cbranch_execz .LBB0_910
	s_bcnt1_i32_b64 s0, s[8:9]
	v_mov_b32_e32 v3, s0
	global_atomic_add v3, v2, v3, s[6:7] offset:32 sc0
